# SwiGLU epilogue: software-pipelined over row-group pairs, transcendental and packed instructions alternating 1:1
# baseline (speedup 1.0000x reference)
.LBB0_127:
	s_waitcnt lgkmcnt(0)
	s_mov_b32 s98, 0x16000
	s_mov_b32 s99, 0
	s_mov_b32 s100, 0x6e000
	s_mov_b32 s101, 0
	v_mov_b64_e32 v[184:185], s[64:65]
	v_lshl_or_b32 v186, s54, 7, v177
	v_mad_u64_u32 v[182:183], s[52:53], v164, s27, v[184:185]
	v_ashrrev_i32_e32 v187, 31, v186
	v_lshlrev_b64 v[186:187], 1, v[186:187]
	v_mul_f32_e32 v130, 0xbfb8aa3b, v170
	v_mul_f32_e32 v131, v170, v170
	v_mul_f32_e32 v168, 0xbfb8aa3b, v171
	v_mul_f32_e32 v169, v171, v171
	v_lshl_add_u64 v[182:183], v[182:183], 0, v[186:187]
	v_pk_mul_f32 v[120:121], v[124:125], v[120:121]
	v_pk_mul_f32 v[104:105], v[108:109], v[104:105]
	v_pk_mul_f32 v[122:123], v[126:127], v[122:123]
	v_pk_mul_f32 v[106:107], v[110:111], v[106:107]
	v_pk_mul_f32 v[112:113], v[116:117], v[112:113]
	v_pk_mul_f32 v[96:97], v[100:101], v[96:97]
	v_pk_mul_f32 v[114:115], v[118:119], v[114:115]
	v_pk_mul_f32 v[98:99], v[102:103], v[98:99]
	v_rcp_f32_e32 v188, v131
	v_rcp_f32_e32 v190, v169
	v_pk_mul_f32 v[124:125], v[124:125], v[130:131] op_sel_hi:[1,0]
	v_pk_mul_f32 v[108:109], v[108:109], v[168:169] op_sel_hi:[1,0]
	v_pk_mul_f32 v[126:127], v[126:127], v[130:131] op_sel_hi:[1,0]
	v_pk_mul_f32 v[110:111], v[110:111], v[168:169] op_sel_hi:[1,0]
	v_pk_mul_f32 v[116:117], v[116:117], v[130:131] op_sel_hi:[1,0]
	v_pk_mul_f32 v[100:101], v[100:101], v[168:169] op_sel_hi:[1,0]
	v_pk_mul_f32 v[118:119], v[118:119], v[130:131] op_sel_hi:[1,0]
	v_pk_mul_f32 v[102:103], v[102:103], v[168:169] op_sel_hi:[1,0]
	v_exp_f32_e32 v124, v124
	v_mul_f32_e32 v130, 0xbfb8aa3b, v166
	v_mul_f32_e32 v131, v166, v166
	v_exp_f32_e32 v125, v125
	v_mul_f32_e32 v168, 0xbfb8aa3b, v167
	v_exp_f32_e32 v108, v108
	v_mul_f32_e32 v169, v167, v167
	v_pk_mul_f32 v[88:89], v[92:93], v[88:89]
	v_exp_f32_e32 v109, v109
	v_pk_mul_f32 v[72:73], v[76:77], v[72:73]
	v_exp_f32_e32 v126, v126
	v_pk_mul_f32 v[90:91], v[94:95], v[90:91]
	v_exp_f32_e32 v127, v127
	v_pk_mul_f32 v[74:75], v[78:79], v[74:75]
	v_pk_mul_f32 v[80:81], v[84:85], v[80:81]
	v_exp_f32_e32 v110, v110
	v_pk_mul_f32 v[64:65], v[68:69], v[64:65]
	v_exp_f32_e32 v111, v111
	v_pk_mul_f32 v[82:83], v[86:87], v[82:83]
	v_exp_f32_e32 v116, v116
	v_pk_mul_f32 v[66:67], v[70:71], v[66:67]
	v_rcp_f32_e32 v192, v131
	v_exp_f32_e32 v117, v117
	v_rcp_f32_e32 v194, v169
	v_exp_f32_e32 v100, v100
	v_pk_mul_f32 v[92:93], v[92:93], v[130:131] op_sel_hi:[1,0]
	v_pk_mul_f32 v[76:77], v[76:77], v[168:169] op_sel_hi:[1,0]
	v_exp_f32_e32 v101, v101
	v_pk_mul_f32 v[94:95], v[94:95], v[130:131] op_sel_hi:[1,0]
	v_exp_f32_e32 v118, v118
	v_pk_mul_f32 v[78:79], v[78:79], v[168:169] op_sel_hi:[1,0]
	v_exp_f32_e32 v119, v119
	v_pk_mul_f32 v[84:85], v[84:85], v[130:131] op_sel_hi:[1,0]
	v_pk_mul_f32 v[68:69], v[68:69], v[168:169] op_sel_hi:[1,0]
	v_exp_f32_e32 v102, v102
	v_pk_mul_f32 v[86:87], v[86:87], v[130:131] op_sel_hi:[1,0]
	v_exp_f32_e32 v103, v103
	v_pk_mul_f32 v[70:71], v[70:71], v[168:169] op_sel_hi:[1,0]
	v_exp_f32_e32 v92, v92
	v_pk_fma_f32 v[124:125], v[124:125], v[188:189], v[188:189] op_sel_hi:[1,0,0]
	v_exp_f32_e32 v93, v93
	v_exp_f32_e32 v76, v76
	v_pk_fma_f32 v[108:109], v[108:109], v[190:191], v[190:191] op_sel_hi:[1,0,0]
	v_exp_f32_e32 v77, v77
	v_exp_f32_e32 v94, v94
	v_pk_fma_f32 v[126:127], v[126:127], v[188:189], v[188:189] op_sel_hi:[1,0,0]
	v_exp_f32_e32 v95, v95
	v_exp_f32_e32 v78, v78
	v_pk_fma_f32 v[110:111], v[110:111], v[190:191], v[190:191] op_sel_hi:[1,0,0]
	v_exp_f32_e32 v79, v79
	v_exp_f32_e32 v84, v84
	v_pk_fma_f32 v[116:117], v[116:117], v[188:189], v[188:189] op_sel_hi:[1,0,0]
	v_exp_f32_e32 v85, v85
	v_exp_f32_e32 v68, v68
	v_pk_fma_f32 v[100:101], v[100:101], v[190:191], v[190:191] op_sel_hi:[1,0,0]
	v_exp_f32_e32 v69, v69
	v_exp_f32_e32 v86, v86
	v_pk_fma_f32 v[118:119], v[118:119], v[188:189], v[188:189] op_sel_hi:[1,0,0]
	v_exp_f32_e32 v87, v87
	v_exp_f32_e32 v70, v70
	v_pk_fma_f32 v[102:103], v[102:103], v[190:191], v[190:191] op_sel_hi:[1,0,0]
	v_exp_f32_e32 v71, v71
	v_rcp_f32_e32 v124, v124
	v_pk_fma_f32 v[92:93], v[92:93], v[192:193], v[192:193] op_sel_hi:[1,0,0]
	v_pk_fma_f32 v[76:77], v[76:77], v[194:195], v[194:195] op_sel_hi:[1,0,0]
	v_rcp_f32_e32 v125, v125
	v_pk_fma_f32 v[94:95], v[94:95], v[192:193], v[192:193] op_sel_hi:[1,0,0]
	v_pk_fma_f32 v[78:79], v[78:79], v[194:195], v[194:195] op_sel_hi:[1,0,0]
	v_rcp_f32_e32 v108, v108
	v_pk_fma_f32 v[84:85], v[84:85], v[192:193], v[192:193] op_sel_hi:[1,0,0]
	v_pk_fma_f32 v[68:69], v[68:69], v[194:195], v[194:195] op_sel_hi:[1,0,0]
	v_rcp_f32_e32 v109, v109
	v_pk_fma_f32 v[86:87], v[86:87], v[192:193], v[192:193] op_sel_hi:[1,0,0]
	v_pk_fma_f32 v[70:71], v[70:71], v[194:195], v[194:195] op_sel_hi:[1,0,0]
	v_rcp_f32_e32 v126, v126
	v_mul_f32_e32 v130, 0xbfb8aa3b, v162
	v_mul_f32_e32 v131, v162, v162
	v_rcp_f32_e32 v127, v127
	v_mul_f32_e32 v168, 0xbfb8aa3b, v163
	v_mul_f32_e32 v169, v163, v163
	v_rcp_f32_e32 v110, v110
	v_pk_mul_f32 v[56:57], v[60:61], v[56:57]
	v_pk_mul_f32 v[40:41], v[44:45], v[40:41]
	v_rcp_f32_e32 v111, v111
	v_pk_mul_f32 v[58:59], v[62:63], v[58:59]
	v_rcp_f32_e32 v116, v116
	v_pk_mul_f32 v[42:43], v[46:47], v[42:43]
	v_pk_mul_f32 v[48:49], v[52:53], v[48:49]
	v_rcp_f32_e32 v117, v117
	v_pk_mul_f32 v[32:33], v[36:37], v[32:33]
	v_pk_mul_f32 v[50:51], v[54:55], v[50:51]
	v_rcp_f32_e32 v100, v100
	v_pk_mul_f32 v[34:35], v[38:39], v[34:35]
	v_rcp_f32_e32 v196, v131
	v_rcp_f32_e32 v101, v101
	v_rcp_f32_e32 v198, v169
	v_pk_mul_f32 v[60:61], v[60:61], v[130:131] op_sel_hi:[1,0]
	v_rcp_f32_e32 v118, v118
	v_pk_mul_f32 v[44:45], v[44:45], v[168:169] op_sel_hi:[1,0]
	v_pk_mul_f32 v[62:63], v[62:63], v[130:131] op_sel_hi:[1,0]
	v_rcp_f32_e32 v119, v119
	v_pk_mul_f32 v[46:47], v[46:47], v[168:169] op_sel_hi:[1,0]
	v_pk_mul_f32 v[52:53], v[52:53], v[130:131] op_sel_hi:[1,0]
	v_rcp_f32_e32 v102, v102
	v_pk_mul_f32 v[36:37], v[36:37], v[168:169] op_sel_hi:[1,0]
	v_pk_mul_f32 v[54:55], v[54:55], v[130:131] op_sel_hi:[1,0]
	v_rcp_f32_e32 v103, v103
	v_pk_mul_f32 v[38:39], v[38:39], v[168:169] op_sel_hi:[1,0]
	v_exp_f32_e32 v60, v60
	v_pk_mul_f32 v[120:121], v[120:121], v[124:125]
	v_pk_mul_f32 v[104:105], v[104:105], v[108:109]
	v_exp_f32_e32 v61, v61
	v_pk_mul_f32 v[122:123], v[122:123], v[126:127]
	v_exp_f32_e32 v44, v44
	v_pk_mul_f32 v[106:107], v[106:107], v[110:111]
	v_exp_f32_e32 v45, v45
	v_pk_mul_f32 v[112:113], v[112:113], v[116:117]
	v_exp_f32_e32 v62, v62
	v_pk_mul_f32 v[96:97], v[96:97], v[100:101]
	v_pk_mul_f32 v[114:115], v[114:115], v[118:119]
	v_exp_f32_e32 v63, v63
	v_pk_mul_f32 v[98:99], v[98:99], v[102:103]
	v_exp_f32_e32 v46, v46
	v_cvt_pk_bf16_f32 v116, v120, v121
	v_exp_f32_e32 v47, v47
	v_cvt_pk_bf16_f32 v117, v122, v123
	v_exp_f32_e32 v52, v52
	v_cvt_pk_bf16_f32 v118, v112, v113
	v_cvt_pk_bf16_f32 v119, v114, v115
	v_exp_f32_e32 v53, v53
	v_cvt_pk_bf16_f32 v100, v104, v105
	v_exp_f32_e32 v36, v36
	v_cvt_pk_bf16_f32 v101, v106, v107
	v_exp_f32_e32 v37, v37
	v_cvt_pk_bf16_f32 v102, v96, v97
	v_exp_f32_e32 v54, v54
	v_cvt_pk_bf16_f32 v103, v98, v99
	global_store_dwordx4 v[182:183], v[116:119], off
	v_exp_f32_e32 v55, v55
	v_lshl_add_u64 v[182:183], v[182:183], 0, s[98:99]
	v_exp_f32_e32 v38, v38
	global_store_dwordx4 v[182:183], v[100:103], off
	v_exp_f32_e32 v39, v39
	v_lshl_add_u64 v[182:183], v[182:183], 0, s[98:99]
	v_rcp_f32_e32 v92, v92
	v_pk_fma_f32 v[60:61], v[60:61], v[196:197], v[196:197] op_sel_hi:[1,0,0]
	v_pk_fma_f32 v[44:45], v[44:45], v[198:199], v[198:199] op_sel_hi:[1,0,0]
	v_rcp_f32_e32 v93, v93
	v_pk_fma_f32 v[62:63], v[62:63], v[196:197], v[196:197] op_sel_hi:[1,0,0]
	v_pk_fma_f32 v[46:47], v[46:47], v[198:199], v[198:199] op_sel_hi:[1,0,0]
	v_rcp_f32_e32 v76, v76
	v_pk_fma_f32 v[52:53], v[52:53], v[196:197], v[196:197] op_sel_hi:[1,0,0]
	v_pk_fma_f32 v[36:37], v[36:37], v[198:199], v[198:199] op_sel_hi:[1,0,0]
	v_rcp_f32_e32 v77, v77
	v_pk_fma_f32 v[54:55], v[54:55], v[196:197], v[196:197] op_sel_hi:[1,0,0]
	v_pk_fma_f32 v[38:39], v[38:39], v[198:199], v[198:199] op_sel_hi:[1,0,0]
	v_rcp_f32_e32 v94, v94
	v_mul_f32_e32 v130, 0xbfb8aa3b, v132
	v_mul_f32_e32 v131, v132, v132
	v_rcp_f32_e32 v95, v95
	v_mul_f32_e32 v168, 0xbfb8aa3b, v133
	v_mul_f32_e32 v169, v133, v133
	v_rcp_f32_e32 v78, v78
	v_pk_mul_f32 v[24:25], v[28:29], v[24:25]
	v_pk_mul_f32 v[8:9], v[12:13], v[8:9]
	v_rcp_f32_e32 v79, v79
	v_pk_mul_f32 v[26:27], v[30:31], v[26:27]
	v_rcp_f32_e32 v84, v84
	v_pk_mul_f32 v[10:11], v[14:15], v[10:11]
	v_pk_mul_f32 v[16:17], v[20:21], v[16:17]
	v_rcp_f32_e32 v85, v85
	v_pk_mul_f32 v[0:1], v[4:5], v[0:1]
	v_pk_mul_f32 v[18:19], v[22:23], v[18:19]
	v_rcp_f32_e32 v68, v68
	v_pk_mul_f32 v[2:3], v[6:7], v[2:3]
	v_rcp_f32_e32 v200, v131
	v_rcp_f32_e32 v69, v69
	v_rcp_f32_e32 v202, v169
	v_pk_mul_f32 v[28:29], v[28:29], v[130:131] op_sel_hi:[1,0]
	v_rcp_f32_e32 v86, v86
	v_pk_mul_f32 v[12:13], v[12:13], v[168:169] op_sel_hi:[1,0]
	v_pk_mul_f32 v[30:31], v[30:31], v[130:131] op_sel_hi:[1,0]
	v_rcp_f32_e32 v87, v87
	v_pk_mul_f32 v[14:15], v[14:15], v[168:169] op_sel_hi:[1,0]
	v_pk_mul_f32 v[20:21], v[20:21], v[130:131] op_sel_hi:[1,0]
	v_rcp_f32_e32 v70, v70
	v_pk_mul_f32 v[4:5], v[4:5], v[168:169] op_sel_hi:[1,0]
	v_pk_mul_f32 v[22:23], v[22:23], v[130:131] op_sel_hi:[1,0]
	v_rcp_f32_e32 v71, v71
	v_pk_mul_f32 v[6:7], v[6:7], v[168:169] op_sel_hi:[1,0]
	v_exp_f32_e32 v28, v28
	v_pk_mul_f32 v[88:89], v[88:89], v[92:93]
	v_pk_mul_f32 v[72:73], v[72:73], v[76:77]
	v_exp_f32_e32 v29, v29
	v_pk_mul_f32 v[90:91], v[90:91], v[94:95]
	v_exp_f32_e32 v12, v12
	v_pk_mul_f32 v[74:75], v[74:75], v[78:79]
	v_exp_f32_e32 v13, v13
	v_pk_mul_f32 v[80:81], v[80:81], v[84:85]
	v_exp_f32_e32 v30, v30
	v_pk_mul_f32 v[64:65], v[64:65], v[68:69]
	v_pk_mul_f32 v[82:83], v[82:83], v[86:87]
	v_exp_f32_e32 v31, v31
	v_pk_mul_f32 v[66:67], v[66:67], v[70:71]
	v_exp_f32_e32 v14, v14
	v_cvt_pk_bf16_f32 v84, v88, v89
	v_exp_f32_e32 v15, v15
	v_cvt_pk_bf16_f32 v85, v90, v91
	v_exp_f32_e32 v20, v20
	v_cvt_pk_bf16_f32 v86, v80, v81
	v_cvt_pk_bf16_f32 v87, v82, v83
	v_exp_f32_e32 v21, v21
	v_cvt_pk_bf16_f32 v68, v72, v73
	v_exp_f32_e32 v4, v4
	v_cvt_pk_bf16_f32 v69, v74, v75
	v_exp_f32_e32 v5, v5
	v_cvt_pk_bf16_f32 v70, v64, v65
	v_exp_f32_e32 v22, v22
	v_cvt_pk_bf16_f32 v71, v66, v67
	global_store_dwordx4 v[182:183], v[84:87], off
	v_exp_f32_e32 v23, v23
	v_lshl_add_u64 v[182:183], v[182:183], 0, s[98:99]
	v_exp_f32_e32 v6, v6
	global_store_dwordx4 v[182:183], v[68:71], off
	v_exp_f32_e32 v7, v7
	v_lshl_add_u64 v[182:183], v[182:183], 0, s[100:101]
	v_rcp_f32_e32 v60, v60
	v_pk_fma_f32 v[28:29], v[28:29], v[200:201], v[200:201] op_sel_hi:[1,0,0]
	v_rcp_f32_e32 v61, v61
	v_rcp_f32_e32 v44, v44
	v_pk_fma_f32 v[12:13], v[12:13], v[202:203], v[202:203] op_sel_hi:[1,0,0]
	v_rcp_f32_e32 v45, v45
	v_rcp_f32_e32 v62, v62
	v_pk_fma_f32 v[30:31], v[30:31], v[200:201], v[200:201] op_sel_hi:[1,0,0]
	v_rcp_f32_e32 v63, v63
	v_rcp_f32_e32 v46, v46
	v_pk_fma_f32 v[14:15], v[14:15], v[202:203], v[202:203] op_sel_hi:[1,0,0]
	v_rcp_f32_e32 v47, v47
	v_rcp_f32_e32 v52, v52
	v_pk_fma_f32 v[20:21], v[20:21], v[200:201], v[200:201] op_sel_hi:[1,0,0]
	v_rcp_f32_e32 v53, v53
	v_rcp_f32_e32 v36, v36
	v_pk_fma_f32 v[4:5], v[4:5], v[202:203], v[202:203] op_sel_hi:[1,0,0]
	v_rcp_f32_e32 v37, v37
	v_rcp_f32_e32 v54, v54
	v_pk_fma_f32 v[22:23], v[22:23], v[200:201], v[200:201] op_sel_hi:[1,0,0]
	v_rcp_f32_e32 v55, v55
	v_rcp_f32_e32 v38, v38
	v_pk_fma_f32 v[6:7], v[6:7], v[202:203], v[202:203] op_sel_hi:[1,0,0]
	v_rcp_f32_e32 v39, v39
	v_rcp_f32_e32 v28, v28
	v_pk_mul_f32 v[56:57], v[56:57], v[60:61]
	v_pk_mul_f32 v[40:41], v[40:41], v[44:45]
	v_rcp_f32_e32 v29, v29
	v_pk_mul_f32 v[58:59], v[58:59], v[62:63]
	v_rcp_f32_e32 v12, v12
	v_pk_mul_f32 v[42:43], v[42:43], v[46:47]
	v_rcp_f32_e32 v13, v13
	v_pk_mul_f32 v[48:49], v[48:49], v[52:53]
	v_rcp_f32_e32 v30, v30
	v_pk_mul_f32 v[32:33], v[32:33], v[36:37]
	v_pk_mul_f32 v[50:51], v[50:51], v[54:55]
	v_rcp_f32_e32 v31, v31
	v_pk_mul_f32 v[34:35], v[34:35], v[38:39]
	v_rcp_f32_e32 v14, v14
	v_cvt_pk_bf16_f32 v52, v56, v57
	v_rcp_f32_e32 v15, v15
	v_cvt_pk_bf16_f32 v53, v58, v59
	v_rcp_f32_e32 v20, v20
	v_cvt_pk_bf16_f32 v54, v48, v49
	v_cvt_pk_bf16_f32 v55, v50, v51
	v_rcp_f32_e32 v21, v21
	v_cvt_pk_bf16_f32 v36, v40, v41
	v_rcp_f32_e32 v4, v4
	v_cvt_pk_bf16_f32 v37, v42, v43
	v_rcp_f32_e32 v5, v5
	v_cvt_pk_bf16_f32 v38, v32, v33
	v_rcp_f32_e32 v22, v22
	v_cvt_pk_bf16_f32 v39, v34, v35
	global_store_dwordx4 v[182:183], v[52:55], off
	v_rcp_f32_e32 v23, v23
	v_lshl_add_u64 v[182:183], v[182:183], 0, s[98:99]
	v_rcp_f32_e32 v6, v6
	global_store_dwordx4 v[182:183], v[36:39], off
	v_rcp_f32_e32 v7, v7
	v_lshl_add_u64 v[182:183], v[182:183], 0, s[98:99]
	v_pk_mul_f32 v[24:25], v[24:25], v[28:29]
	v_pk_mul_f32 v[8:9], v[8:9], v[12:13]
	v_pk_mul_f32 v[26:27], v[26:27], v[30:31]
	v_pk_mul_f32 v[10:11], v[10:11], v[14:15]
	v_pk_mul_f32 v[16:17], v[16:17], v[20:21]
	v_pk_mul_f32 v[0:1], v[0:1], v[4:5]
	v_pk_mul_f32 v[18:19], v[18:19], v[22:23]
	v_pk_mul_f32 v[2:3], v[2:3], v[6:7]
	v_cvt_pk_bf16_f32 v20, v24, v25
	v_cvt_pk_bf16_f32 v21, v26, v27
	v_cvt_pk_bf16_f32 v22, v16, v17
	v_cvt_pk_bf16_f32 v23, v18, v19
	v_cvt_pk_bf16_f32 v4, v8, v9
	v_cvt_pk_bf16_f32 v5, v10, v11
	v_cvt_pk_bf16_f32 v6, v0, v1
	v_cvt_pk_bf16_f32 v7, v2, v3
	global_store_dwordx4 v[182:183], v[20:23], off
	v_lshl_add_u64 v[182:183], v[182:183], 0, s[98:99]
	global_store_dwordx4 v[182:183], v[4:7], off
	s_andn2_b64 vcc, exec, s[6:7]
	s_mov_b64 s[6:7], -1
	s_cbranch_vccnz .LBB0_116
	s_andn2_b64 vcc, exec, s[10:11]
	s_cbranch_vccnz .LBB0_115
	s_barrier
	s_branch .LBB0_115

.LBB0_1155:
	s_waitcnt lgkmcnt(0)
	s_mov_b32 s98, 0x16000
	s_mov_b32 s99, 0
	s_mov_b32 s100, 0x6e000
	s_mov_b32 s101, 0
	v_mov_b64_e32 v[184:185], s[64:65]
	v_lshl_or_b32 v186, s56, 7, v173
	v_mad_u64_u32 v[182:183], s[54:55], v160, s27, v[184:185]
	v_ashrrev_i32_e32 v187, 31, v186
	v_lshlrev_b64 v[186:187], 1, v[186:187]
	v_mul_f32_e32 v178, 0xbfb8aa3b, v166
	v_mul_f32_e32 v179, v166, v166
	v_mul_f32_e32 v180, 0xbfb8aa3b, v167
	v_mul_f32_e32 v181, v167, v167
	v_lshl_add_u64 v[182:183], v[182:183], 0, v[186:187]
	v_pk_mul_f32 v[120:121], v[124:125], v[120:121]
	v_pk_mul_f32 v[104:105], v[108:109], v[104:105]
	v_pk_mul_f32 v[122:123], v[126:127], v[122:123]
	v_pk_mul_f32 v[106:107], v[110:111], v[106:107]
	v_pk_mul_f32 v[112:113], v[116:117], v[112:113]
	v_pk_mul_f32 v[96:97], v[100:101], v[96:97]
	v_pk_mul_f32 v[114:115], v[118:119], v[114:115]
	v_pk_mul_f32 v[98:99], v[102:103], v[98:99]
	v_rcp_f32_e32 v188, v179
	v_rcp_f32_e32 v190, v181
	v_pk_mul_f32 v[124:125], v[124:125], v[178:179] op_sel_hi:[1,0]
	v_pk_mul_f32 v[108:109], v[108:109], v[180:181] op_sel_hi:[1,0]
	v_pk_mul_f32 v[126:127], v[126:127], v[178:179] op_sel_hi:[1,0]
	v_pk_mul_f32 v[110:111], v[110:111], v[180:181] op_sel_hi:[1,0]
	v_pk_mul_f32 v[116:117], v[116:117], v[178:179] op_sel_hi:[1,0]
	v_pk_mul_f32 v[100:101], v[100:101], v[180:181] op_sel_hi:[1,0]
	v_pk_mul_f32 v[118:119], v[118:119], v[178:179] op_sel_hi:[1,0]
	v_pk_mul_f32 v[102:103], v[102:103], v[180:181] op_sel_hi:[1,0]
	v_exp_f32_e32 v124, v124
	v_mul_f32_e32 v178, 0xbfb8aa3b, v162
	v_mul_f32_e32 v179, v162, v162
	v_exp_f32_e32 v125, v125
	v_mul_f32_e32 v180, 0xbfb8aa3b, v163
	v_exp_f32_e32 v108, v108
	v_mul_f32_e32 v181, v163, v163
	v_pk_mul_f32 v[88:89], v[92:93], v[88:89]
	v_exp_f32_e32 v109, v109
	v_pk_mul_f32 v[72:73], v[76:77], v[72:73]
	v_exp_f32_e32 v126, v126
	v_pk_mul_f32 v[90:91], v[94:95], v[90:91]
	v_exp_f32_e32 v127, v127
	v_pk_mul_f32 v[74:75], v[78:79], v[74:75]
	v_pk_mul_f32 v[80:81], v[84:85], v[80:81]
	v_exp_f32_e32 v110, v110
	v_pk_mul_f32 v[64:65], v[68:69], v[64:65]
	v_exp_f32_e32 v111, v111
	v_pk_mul_f32 v[82:83], v[86:87], v[82:83]
	v_exp_f32_e32 v116, v116
	v_pk_mul_f32 v[66:67], v[70:71], v[66:67]
	v_rcp_f32_e32 v192, v179
	v_exp_f32_e32 v117, v117
	v_rcp_f32_e32 v194, v181
	v_exp_f32_e32 v100, v100
	v_pk_mul_f32 v[92:93], v[92:93], v[178:179] op_sel_hi:[1,0]
	v_pk_mul_f32 v[76:77], v[76:77], v[180:181] op_sel_hi:[1,0]
	v_exp_f32_e32 v101, v101
	v_pk_mul_f32 v[94:95], v[94:95], v[178:179] op_sel_hi:[1,0]
	v_exp_f32_e32 v118, v118
	v_pk_mul_f32 v[78:79], v[78:79], v[180:181] op_sel_hi:[1,0]
	v_exp_f32_e32 v119, v119
	v_pk_mul_f32 v[84:85], v[84:85], v[178:179] op_sel_hi:[1,0]
	v_pk_mul_f32 v[68:69], v[68:69], v[180:181] op_sel_hi:[1,0]
	v_exp_f32_e32 v102, v102
	v_pk_mul_f32 v[86:87], v[86:87], v[178:179] op_sel_hi:[1,0]
	v_exp_f32_e32 v103, v103
	v_pk_mul_f32 v[70:71], v[70:71], v[180:181] op_sel_hi:[1,0]
	v_exp_f32_e32 v92, v92
	v_pk_fma_f32 v[124:125], v[124:125], v[188:189], v[188:189] op_sel_hi:[1,0,0]
	v_exp_f32_e32 v93, v93
	v_exp_f32_e32 v76, v76
	v_pk_fma_f32 v[108:109], v[108:109], v[190:191], v[190:191] op_sel_hi:[1,0,0]
	v_exp_f32_e32 v77, v77
	v_exp_f32_e32 v94, v94
	v_pk_fma_f32 v[126:127], v[126:127], v[188:189], v[188:189] op_sel_hi:[1,0,0]
	v_exp_f32_e32 v95, v95
	v_exp_f32_e32 v78, v78
	v_pk_fma_f32 v[110:111], v[110:111], v[190:191], v[190:191] op_sel_hi:[1,0,0]
	v_exp_f32_e32 v79, v79
	v_exp_f32_e32 v84, v84
	v_pk_fma_f32 v[116:117], v[116:117], v[188:189], v[188:189] op_sel_hi:[1,0,0]
	v_exp_f32_e32 v85, v85
	v_exp_f32_e32 v68, v68
	v_pk_fma_f32 v[100:101], v[100:101], v[190:191], v[190:191] op_sel_hi:[1,0,0]
	v_exp_f32_e32 v69, v69
	v_exp_f32_e32 v86, v86
	v_pk_fma_f32 v[118:119], v[118:119], v[188:189], v[188:189] op_sel_hi:[1,0,0]
	v_exp_f32_e32 v87, v87
	v_exp_f32_e32 v70, v70
	v_pk_fma_f32 v[102:103], v[102:103], v[190:191], v[190:191] op_sel_hi:[1,0,0]
	v_exp_f32_e32 v71, v71
	v_rcp_f32_e32 v124, v124
	v_pk_fma_f32 v[92:93], v[92:93], v[192:193], v[192:193] op_sel_hi:[1,0,0]
	v_pk_fma_f32 v[76:77], v[76:77], v[194:195], v[194:195] op_sel_hi:[1,0,0]
	v_rcp_f32_e32 v125, v125
	v_pk_fma_f32 v[94:95], v[94:95], v[192:193], v[192:193] op_sel_hi:[1,0,0]
	v_pk_fma_f32 v[78:79], v[78:79], v[194:195], v[194:195] op_sel_hi:[1,0,0]
	v_rcp_f32_e32 v108, v108
	v_pk_fma_f32 v[84:85], v[84:85], v[192:193], v[192:193] op_sel_hi:[1,0,0]
	v_pk_fma_f32 v[68:69], v[68:69], v[194:195], v[194:195] op_sel_hi:[1,0,0]
	v_rcp_f32_e32 v109, v109
	v_pk_fma_f32 v[86:87], v[86:87], v[192:193], v[192:193] op_sel_hi:[1,0,0]
	v_pk_fma_f32 v[70:71], v[70:71], v[194:195], v[194:195] op_sel_hi:[1,0,0]
	v_rcp_f32_e32 v126, v126
	v_mul_f32_e32 v178, 0xbfb8aa3b, v154
	v_mul_f32_e32 v179, v154, v154
	v_rcp_f32_e32 v127, v127
	v_mul_f32_e32 v180, 0xbfb8aa3b, v155
	v_mul_f32_e32 v181, v155, v155
	v_rcp_f32_e32 v110, v110
	v_pk_mul_f32 v[56:57], v[60:61], v[56:57]
	v_pk_mul_f32 v[40:41], v[44:45], v[40:41]
	v_rcp_f32_e32 v111, v111
	v_pk_mul_f32 v[58:59], v[62:63], v[58:59]
	v_rcp_f32_e32 v116, v116
	v_pk_mul_f32 v[42:43], v[46:47], v[42:43]
	v_pk_mul_f32 v[48:49], v[52:53], v[48:49]
	v_rcp_f32_e32 v117, v117
	v_pk_mul_f32 v[32:33], v[36:37], v[32:33]
	v_pk_mul_f32 v[50:51], v[54:55], v[50:51]
	v_rcp_f32_e32 v100, v100
	v_pk_mul_f32 v[34:35], v[38:39], v[34:35]
	v_rcp_f32_e32 v196, v179
	v_rcp_f32_e32 v101, v101
	v_rcp_f32_e32 v198, v181
	v_pk_mul_f32 v[60:61], v[60:61], v[178:179] op_sel_hi:[1,0]
	v_rcp_f32_e32 v118, v118
	v_pk_mul_f32 v[44:45], v[44:45], v[180:181] op_sel_hi:[1,0]
	v_pk_mul_f32 v[62:63], v[62:63], v[178:179] op_sel_hi:[1,0]
	v_rcp_f32_e32 v119, v119
	v_pk_mul_f32 v[46:47], v[46:47], v[180:181] op_sel_hi:[1,0]
	v_pk_mul_f32 v[52:53], v[52:53], v[178:179] op_sel_hi:[1,0]
	v_rcp_f32_e32 v102, v102
	v_pk_mul_f32 v[36:37], v[36:37], v[180:181] op_sel_hi:[1,0]
	v_pk_mul_f32 v[54:55], v[54:55], v[178:179] op_sel_hi:[1,0]
	v_rcp_f32_e32 v103, v103
	v_pk_mul_f32 v[38:39], v[38:39], v[180:181] op_sel_hi:[1,0]
	v_exp_f32_e32 v60, v60
	v_pk_mul_f32 v[120:121], v[120:121], v[124:125]
	v_pk_mul_f32 v[104:105], v[104:105], v[108:109]
	v_exp_f32_e32 v61, v61
	v_pk_mul_f32 v[122:123], v[122:123], v[126:127]
	v_exp_f32_e32 v44, v44
	v_pk_mul_f32 v[106:107], v[106:107], v[110:111]
	v_exp_f32_e32 v45, v45
	v_pk_mul_f32 v[112:113], v[112:113], v[116:117]
	v_exp_f32_e32 v62, v62
	v_pk_mul_f32 v[96:97], v[96:97], v[100:101]
	v_pk_mul_f32 v[114:115], v[114:115], v[118:119]
	v_exp_f32_e32 v63, v63
	v_pk_mul_f32 v[98:99], v[98:99], v[102:103]
	v_exp_f32_e32 v46, v46
	v_cvt_pk_bf16_f32 v116, v120, v121
	v_exp_f32_e32 v47, v47
	v_cvt_pk_bf16_f32 v117, v122, v123
	v_exp_f32_e32 v52, v52
	v_cvt_pk_bf16_f32 v118, v112, v113
	v_cvt_pk_bf16_f32 v119, v114, v115
	v_exp_f32_e32 v53, v53
	v_cvt_pk_bf16_f32 v100, v104, v105
	v_exp_f32_e32 v36, v36
	v_cvt_pk_bf16_f32 v101, v106, v107
	v_exp_f32_e32 v37, v37
	v_cvt_pk_bf16_f32 v102, v96, v97
	v_exp_f32_e32 v54, v54
	v_cvt_pk_bf16_f32 v103, v98, v99
	global_store_dwordx4 v[182:183], v[116:119], off
	v_exp_f32_e32 v55, v55
	v_lshl_add_u64 v[182:183], v[182:183], 0, s[98:99]
	v_exp_f32_e32 v38, v38
	global_store_dwordx4 v[182:183], v[100:103], off
	v_exp_f32_e32 v39, v39
	v_lshl_add_u64 v[182:183], v[182:183], 0, s[98:99]
	v_rcp_f32_e32 v92, v92
	v_pk_fma_f32 v[60:61], v[60:61], v[196:197], v[196:197] op_sel_hi:[1,0,0]
	v_pk_fma_f32 v[44:45], v[44:45], v[198:199], v[198:199] op_sel_hi:[1,0,0]
	v_rcp_f32_e32 v93, v93
	v_pk_fma_f32 v[62:63], v[62:63], v[196:197], v[196:197] op_sel_hi:[1,0,0]
	v_pk_fma_f32 v[46:47], v[46:47], v[198:199], v[198:199] op_sel_hi:[1,0,0]
	v_rcp_f32_e32 v76, v76
	v_pk_fma_f32 v[52:53], v[52:53], v[196:197], v[196:197] op_sel_hi:[1,0,0]
	v_pk_fma_f32 v[36:37], v[36:37], v[198:199], v[198:199] op_sel_hi:[1,0,0]
	v_rcp_f32_e32 v77, v77
	v_pk_fma_f32 v[54:55], v[54:55], v[196:197], v[196:197] op_sel_hi:[1,0,0]
	v_pk_fma_f32 v[38:39], v[38:39], v[198:199], v[198:199] op_sel_hi:[1,0,0]
	v_rcp_f32_e32 v94, v94
	v_mul_f32_e32 v178, 0xbfb8aa3b, v148
	v_mul_f32_e32 v179, v148, v148
	v_rcp_f32_e32 v95, v95
	v_mul_f32_e32 v180, 0xbfb8aa3b, v149
	v_mul_f32_e32 v181, v149, v149
	v_rcp_f32_e32 v78, v78
	v_pk_mul_f32 v[24:25], v[28:29], v[24:25]
	v_pk_mul_f32 v[8:9], v[12:13], v[8:9]
	v_rcp_f32_e32 v79, v79
	v_pk_mul_f32 v[26:27], v[30:31], v[26:27]
	v_rcp_f32_e32 v84, v84
	v_pk_mul_f32 v[10:11], v[14:15], v[10:11]
	v_pk_mul_f32 v[16:17], v[20:21], v[16:17]
	v_rcp_f32_e32 v85, v85
	v_pk_mul_f32 v[0:1], v[4:5], v[0:1]
	v_pk_mul_f32 v[18:19], v[22:23], v[18:19]
	v_rcp_f32_e32 v68, v68
	v_pk_mul_f32 v[2:3], v[6:7], v[2:3]
	v_rcp_f32_e32 v200, v179
	v_rcp_f32_e32 v69, v69
	v_rcp_f32_e32 v202, v181
	v_pk_mul_f32 v[28:29], v[28:29], v[178:179] op_sel_hi:[1,0]
	v_rcp_f32_e32 v86, v86
	v_pk_mul_f32 v[12:13], v[12:13], v[180:181] op_sel_hi:[1,0]
	v_pk_mul_f32 v[30:31], v[30:31], v[178:179] op_sel_hi:[1,0]
	v_rcp_f32_e32 v87, v87
	v_pk_mul_f32 v[14:15], v[14:15], v[180:181] op_sel_hi:[1,0]
	v_pk_mul_f32 v[20:21], v[20:21], v[178:179] op_sel_hi:[1,0]
	v_rcp_f32_e32 v70, v70
	v_pk_mul_f32 v[4:5], v[4:5], v[180:181] op_sel_hi:[1,0]
	v_pk_mul_f32 v[22:23], v[22:23], v[178:179] op_sel_hi:[1,0]
	v_rcp_f32_e32 v71, v71
	v_pk_mul_f32 v[6:7], v[6:7], v[180:181] op_sel_hi:[1,0]
	v_exp_f32_e32 v28, v28
	v_pk_mul_f32 v[88:89], v[88:89], v[92:93]
	v_pk_mul_f32 v[72:73], v[72:73], v[76:77]
	v_exp_f32_e32 v29, v29
	v_pk_mul_f32 v[90:91], v[90:91], v[94:95]
	v_exp_f32_e32 v12, v12
	v_pk_mul_f32 v[74:75], v[74:75], v[78:79]
	v_exp_f32_e32 v13, v13
	v_pk_mul_f32 v[80:81], v[80:81], v[84:85]
	v_exp_f32_e32 v30, v30
	v_pk_mul_f32 v[64:65], v[64:65], v[68:69]
	v_pk_mul_f32 v[82:83], v[82:83], v[86:87]
	v_exp_f32_e32 v31, v31
	v_pk_mul_f32 v[66:67], v[66:67], v[70:71]
	v_exp_f32_e32 v14, v14
	v_cvt_pk_bf16_f32 v84, v88, v89
	v_exp_f32_e32 v15, v15
	v_cvt_pk_bf16_f32 v85, v90, v91
	v_exp_f32_e32 v20, v20
	v_cvt_pk_bf16_f32 v86, v80, v81
	v_cvt_pk_bf16_f32 v87, v82, v83
	v_exp_f32_e32 v21, v21
	v_cvt_pk_bf16_f32 v68, v72, v73
	v_exp_f32_e32 v4, v4
	v_cvt_pk_bf16_f32 v69, v74, v75
	v_exp_f32_e32 v5, v5
	v_cvt_pk_bf16_f32 v70, v64, v65
	v_exp_f32_e32 v22, v22
	v_cvt_pk_bf16_f32 v71, v66, v67
	global_store_dwordx4 v[182:183], v[84:87], off
	v_exp_f32_e32 v23, v23
	v_lshl_add_u64 v[182:183], v[182:183], 0, s[98:99]
	v_exp_f32_e32 v6, v6
	global_store_dwordx4 v[182:183], v[68:71], off
	v_exp_f32_e32 v7, v7
	v_lshl_add_u64 v[182:183], v[182:183], 0, s[100:101]
	v_rcp_f32_e32 v60, v60
	v_pk_fma_f32 v[28:29], v[28:29], v[200:201], v[200:201] op_sel_hi:[1,0,0]
	v_rcp_f32_e32 v61, v61
	v_rcp_f32_e32 v44, v44
	v_pk_fma_f32 v[12:13], v[12:13], v[202:203], v[202:203] op_sel_hi:[1,0,0]
	v_rcp_f32_e32 v45, v45
	v_rcp_f32_e32 v62, v62
	v_pk_fma_f32 v[30:31], v[30:31], v[200:201], v[200:201] op_sel_hi:[1,0,0]
	v_rcp_f32_e32 v63, v63
	v_rcp_f32_e32 v46, v46
	v_pk_fma_f32 v[14:15], v[14:15], v[202:203], v[202:203] op_sel_hi:[1,0,0]
	v_rcp_f32_e32 v47, v47
	v_rcp_f32_e32 v52, v52
	v_pk_fma_f32 v[20:21], v[20:21], v[200:201], v[200:201] op_sel_hi:[1,0,0]
	v_rcp_f32_e32 v53, v53
	v_rcp_f32_e32 v36, v36
	v_pk_fma_f32 v[4:5], v[4:5], v[202:203], v[202:203] op_sel_hi:[1,0,0]
	v_rcp_f32_e32 v37, v37
	v_rcp_f32_e32 v54, v54
	v_pk_fma_f32 v[22:23], v[22:23], v[200:201], v[200:201] op_sel_hi:[1,0,0]
	v_rcp_f32_e32 v55, v55
	v_rcp_f32_e32 v38, v38
	v_pk_fma_f32 v[6:7], v[6:7], v[202:203], v[202:203] op_sel_hi:[1,0,0]
	v_rcp_f32_e32 v39, v39
	v_rcp_f32_e32 v28, v28
	v_pk_mul_f32 v[56:57], v[56:57], v[60:61]
	v_pk_mul_f32 v[40:41], v[40:41], v[44:45]
	v_rcp_f32_e32 v29, v29
	v_pk_mul_f32 v[58:59], v[58:59], v[62:63]
	v_rcp_f32_e32 v12, v12
	v_pk_mul_f32 v[42:43], v[42:43], v[46:47]
	v_rcp_f32_e32 v13, v13
	v_pk_mul_f32 v[48:49], v[48:49], v[52:53]
	v_rcp_f32_e32 v30, v30
	v_pk_mul_f32 v[32:33], v[32:33], v[36:37]
	v_pk_mul_f32 v[50:51], v[50:51], v[54:55]
	v_rcp_f32_e32 v31, v31
	v_pk_mul_f32 v[34:35], v[34:35], v[38:39]
	v_rcp_f32_e32 v14, v14
	v_cvt_pk_bf16_f32 v52, v56, v57
	v_rcp_f32_e32 v15, v15
	v_cvt_pk_bf16_f32 v53, v58, v59
	v_rcp_f32_e32 v20, v20
	v_cvt_pk_bf16_f32 v54, v48, v49
	v_cvt_pk_bf16_f32 v55, v50, v51
	v_rcp_f32_e32 v21, v21
	v_cvt_pk_bf16_f32 v36, v40, v41
	v_rcp_f32_e32 v4, v4
	v_cvt_pk_bf16_f32 v37, v42, v43
	v_rcp_f32_e32 v5, v5
	v_cvt_pk_bf16_f32 v38, v32, v33
	v_rcp_f32_e32 v22, v22
	v_cvt_pk_bf16_f32 v39, v34, v35
	global_store_dwordx4 v[182:183], v[52:55], off
	v_rcp_f32_e32 v23, v23
	v_lshl_add_u64 v[182:183], v[182:183], 0, s[98:99]
	v_rcp_f32_e32 v6, v6
	global_store_dwordx4 v[182:183], v[36:39], off
	v_rcp_f32_e32 v7, v7
	v_lshl_add_u64 v[182:183], v[182:183], 0, s[98:99]
	v_pk_mul_f32 v[24:25], v[24:25], v[28:29]
	v_pk_mul_f32 v[8:9], v[8:9], v[12:13]
	v_pk_mul_f32 v[26:27], v[26:27], v[30:31]
	v_pk_mul_f32 v[10:11], v[10:11], v[14:15]
	v_pk_mul_f32 v[16:17], v[16:17], v[20:21]
	v_pk_mul_f32 v[0:1], v[0:1], v[4:5]
	v_pk_mul_f32 v[18:19], v[18:19], v[22:23]
	v_pk_mul_f32 v[2:3], v[2:3], v[6:7]
	v_cvt_pk_bf16_f32 v20, v24, v25
	v_cvt_pk_bf16_f32 v21, v26, v27
	v_cvt_pk_bf16_f32 v22, v16, v17
	v_cvt_pk_bf16_f32 v23, v18, v19
	v_cvt_pk_bf16_f32 v4, v8, v9
	v_cvt_pk_bf16_f32 v5, v10, v11
	v_cvt_pk_bf16_f32 v6, v0, v1
	v_cvt_pk_bf16_f32 v7, v2, v3
	global_store_dwordx4 v[182:183], v[20:23], off
	v_lshl_add_u64 v[182:183], v[182:183], 0, s[98:99]
	global_store_dwordx4 v[182:183], v[4:7], off
	s_andn2_b64 vcc, exec, s[4:5]
	s_mov_b64 s[4:5], -1
	s_cbranch_vccnz .LBB0_1144
	s_andn2_b64 vcc, exec, s[8:9]
	s_cbranch_vccnz .LBB0_1143
	s_barrier
	s_branch .LBB0_1143

.LBB0_2199:
	s_waitcnt lgkmcnt(0)
	s_mov_b32 s98, 0x16000
	s_mov_b32 s99, 0
	s_mov_b32 s100, 0x6e000
	s_mov_b32 s101, 0
	v_mov_b64_e32 v[184:185], s[64:65]
	v_lshl_or_b32 v186, s56, 7, v173
	v_mad_u64_u32 v[182:183], s[52:53], v160, s54, v[184:185]
	v_ashrrev_i32_e32 v187, 31, v186
	v_lshlrev_b64 v[186:187], 1, v[186:187]
	v_mul_f32_e32 v178, 0xbfb8aa3b, v166
	v_mul_f32_e32 v179, v166, v166
	v_mul_f32_e32 v180, 0xbfb8aa3b, v167
	v_mul_f32_e32 v181, v167, v167
	v_lshl_add_u64 v[182:183], v[182:183], 0, v[186:187]
	v_pk_mul_f32 v[120:121], v[124:125], v[120:121]
	v_pk_mul_f32 v[104:105], v[108:109], v[104:105]
	v_pk_mul_f32 v[122:123], v[126:127], v[122:123]
	v_pk_mul_f32 v[106:107], v[110:111], v[106:107]
	v_pk_mul_f32 v[112:113], v[116:117], v[112:113]
	v_pk_mul_f32 v[96:97], v[100:101], v[96:97]
	v_pk_mul_f32 v[114:115], v[118:119], v[114:115]
	v_pk_mul_f32 v[98:99], v[102:103], v[98:99]
	v_rcp_f32_e32 v188, v179
	v_rcp_f32_e32 v190, v181
	v_pk_mul_f32 v[124:125], v[124:125], v[178:179] op_sel_hi:[1,0]
	v_pk_mul_f32 v[108:109], v[108:109], v[180:181] op_sel_hi:[1,0]
	v_pk_mul_f32 v[126:127], v[126:127], v[178:179] op_sel_hi:[1,0]
	v_pk_mul_f32 v[110:111], v[110:111], v[180:181] op_sel_hi:[1,0]
	v_pk_mul_f32 v[116:117], v[116:117], v[178:179] op_sel_hi:[1,0]
	v_pk_mul_f32 v[100:101], v[100:101], v[180:181] op_sel_hi:[1,0]
	v_pk_mul_f32 v[118:119], v[118:119], v[178:179] op_sel_hi:[1,0]
	v_pk_mul_f32 v[102:103], v[102:103], v[180:181] op_sel_hi:[1,0]
	v_exp_f32_e32 v124, v124
	v_mul_f32_e32 v178, 0xbfb8aa3b, v162
	v_mul_f32_e32 v179, v162, v162
	v_exp_f32_e32 v125, v125
	v_mul_f32_e32 v180, 0xbfb8aa3b, v163
	v_exp_f32_e32 v108, v108
	v_mul_f32_e32 v181, v163, v163
	v_pk_mul_f32 v[88:89], v[92:93], v[88:89]
	v_exp_f32_e32 v109, v109
	v_pk_mul_f32 v[72:73], v[76:77], v[72:73]
	v_exp_f32_e32 v126, v126
	v_pk_mul_f32 v[90:91], v[94:95], v[90:91]
	v_exp_f32_e32 v127, v127
	v_pk_mul_f32 v[74:75], v[78:79], v[74:75]
	v_pk_mul_f32 v[80:81], v[84:85], v[80:81]
	v_exp_f32_e32 v110, v110
	v_pk_mul_f32 v[64:65], v[68:69], v[64:65]
	v_exp_f32_e32 v111, v111
	v_pk_mul_f32 v[82:83], v[86:87], v[82:83]
	v_exp_f32_e32 v116, v116
	v_pk_mul_f32 v[66:67], v[70:71], v[66:67]
	v_rcp_f32_e32 v192, v179
	v_exp_f32_e32 v117, v117
	v_rcp_f32_e32 v194, v181
	v_exp_f32_e32 v100, v100
	v_pk_mul_f32 v[92:93], v[92:93], v[178:179] op_sel_hi:[1,0]
	v_pk_mul_f32 v[76:77], v[76:77], v[180:181] op_sel_hi:[1,0]
	v_exp_f32_e32 v101, v101
	v_pk_mul_f32 v[94:95], v[94:95], v[178:179] op_sel_hi:[1,0]
	v_exp_f32_e32 v118, v118
	v_pk_mul_f32 v[78:79], v[78:79], v[180:181] op_sel_hi:[1,0]
	v_exp_f32_e32 v119, v119
	v_pk_mul_f32 v[84:85], v[84:85], v[178:179] op_sel_hi:[1,0]
	v_pk_mul_f32 v[68:69], v[68:69], v[180:181] op_sel_hi:[1,0]
	v_exp_f32_e32 v102, v102
	v_pk_mul_f32 v[86:87], v[86:87], v[178:179] op_sel_hi:[1,0]
	v_exp_f32_e32 v103, v103
	v_pk_mul_f32 v[70:71], v[70:71], v[180:181] op_sel_hi:[1,0]
	v_exp_f32_e32 v92, v92
	v_pk_fma_f32 v[124:125], v[124:125], v[188:189], v[188:189] op_sel_hi:[1,0,0]
	v_exp_f32_e32 v93, v93
	v_exp_f32_e32 v76, v76
	v_pk_fma_f32 v[108:109], v[108:109], v[190:191], v[190:191] op_sel_hi:[1,0,0]
	v_exp_f32_e32 v77, v77
	v_exp_f32_e32 v94, v94
	v_pk_fma_f32 v[126:127], v[126:127], v[188:189], v[188:189] op_sel_hi:[1,0,0]
	v_exp_f32_e32 v95, v95
	v_exp_f32_e32 v78, v78
	v_pk_fma_f32 v[110:111], v[110:111], v[190:191], v[190:191] op_sel_hi:[1,0,0]
	v_exp_f32_e32 v79, v79
	v_exp_f32_e32 v84, v84
	v_pk_fma_f32 v[116:117], v[116:117], v[188:189], v[188:189] op_sel_hi:[1,0,0]
	v_exp_f32_e32 v85, v85
	v_exp_f32_e32 v68, v68
	v_pk_fma_f32 v[100:101], v[100:101], v[190:191], v[190:191] op_sel_hi:[1,0,0]
	v_exp_f32_e32 v69, v69
	v_exp_f32_e32 v86, v86
	v_pk_fma_f32 v[118:119], v[118:119], v[188:189], v[188:189] op_sel_hi:[1,0,0]
	v_exp_f32_e32 v87, v87
	v_exp_f32_e32 v70, v70
	v_pk_fma_f32 v[102:103], v[102:103], v[190:191], v[190:191] op_sel_hi:[1,0,0]
	v_exp_f32_e32 v71, v71
	v_rcp_f32_e32 v124, v124
	v_pk_fma_f32 v[92:93], v[92:93], v[192:193], v[192:193] op_sel_hi:[1,0,0]
	v_pk_fma_f32 v[76:77], v[76:77], v[194:195], v[194:195] op_sel_hi:[1,0,0]
	v_rcp_f32_e32 v125, v125
	v_pk_fma_f32 v[94:95], v[94:95], v[192:193], v[192:193] op_sel_hi:[1,0,0]
	v_pk_fma_f32 v[78:79], v[78:79], v[194:195], v[194:195] op_sel_hi:[1,0,0]
	v_rcp_f32_e32 v108, v108
	v_pk_fma_f32 v[84:85], v[84:85], v[192:193], v[192:193] op_sel_hi:[1,0,0]
	v_pk_fma_f32 v[68:69], v[68:69], v[194:195], v[194:195] op_sel_hi:[1,0,0]
	v_rcp_f32_e32 v109, v109
	v_pk_fma_f32 v[86:87], v[86:87], v[192:193], v[192:193] op_sel_hi:[1,0,0]
	v_pk_fma_f32 v[70:71], v[70:71], v[194:195], v[194:195] op_sel_hi:[1,0,0]
	v_rcp_f32_e32 v126, v126
	v_mul_f32_e32 v178, 0xbfb8aa3b, v154
	v_mul_f32_e32 v179, v154, v154
	v_rcp_f32_e32 v127, v127
	v_mul_f32_e32 v180, 0xbfb8aa3b, v155
	v_mul_f32_e32 v181, v155, v155
	v_rcp_f32_e32 v110, v110
	v_pk_mul_f32 v[56:57], v[60:61], v[56:57]
	v_pk_mul_f32 v[40:41], v[44:45], v[40:41]
	v_rcp_f32_e32 v111, v111
	v_pk_mul_f32 v[58:59], v[62:63], v[58:59]
	v_rcp_f32_e32 v116, v116
	v_pk_mul_f32 v[42:43], v[46:47], v[42:43]
	v_pk_mul_f32 v[48:49], v[52:53], v[48:49]
	v_rcp_f32_e32 v117, v117
	v_pk_mul_f32 v[32:33], v[36:37], v[32:33]
	v_pk_mul_f32 v[50:51], v[54:55], v[50:51]
	v_rcp_f32_e32 v100, v100
	v_pk_mul_f32 v[34:35], v[38:39], v[34:35]
	v_rcp_f32_e32 v196, v179
	v_rcp_f32_e32 v101, v101
	v_rcp_f32_e32 v198, v181
	v_pk_mul_f32 v[60:61], v[60:61], v[178:179] op_sel_hi:[1,0]
	v_rcp_f32_e32 v118, v118
	v_pk_mul_f32 v[44:45], v[44:45], v[180:181] op_sel_hi:[1,0]
	v_pk_mul_f32 v[62:63], v[62:63], v[178:179] op_sel_hi:[1,0]
	v_rcp_f32_e32 v119, v119
	v_pk_mul_f32 v[46:47], v[46:47], v[180:181] op_sel_hi:[1,0]
	v_pk_mul_f32 v[52:53], v[52:53], v[178:179] op_sel_hi:[1,0]
	v_rcp_f32_e32 v102, v102
	v_pk_mul_f32 v[36:37], v[36:37], v[180:181] op_sel_hi:[1,0]
	v_pk_mul_f32 v[54:55], v[54:55], v[178:179] op_sel_hi:[1,0]
	v_rcp_f32_e32 v103, v103
	v_pk_mul_f32 v[38:39], v[38:39], v[180:181] op_sel_hi:[1,0]
	v_exp_f32_e32 v60, v60
	v_pk_mul_f32 v[120:121], v[120:121], v[124:125]
	v_pk_mul_f32 v[104:105], v[104:105], v[108:109]
	v_exp_f32_e32 v61, v61
	v_pk_mul_f32 v[122:123], v[122:123], v[126:127]
	v_exp_f32_e32 v44, v44
	v_pk_mul_f32 v[106:107], v[106:107], v[110:111]
	v_exp_f32_e32 v45, v45
	v_pk_mul_f32 v[112:113], v[112:113], v[116:117]
	v_exp_f32_e32 v62, v62
	v_pk_mul_f32 v[96:97], v[96:97], v[100:101]
	v_pk_mul_f32 v[114:115], v[114:115], v[118:119]
	v_exp_f32_e32 v63, v63
	v_pk_mul_f32 v[98:99], v[98:99], v[102:103]
	v_exp_f32_e32 v46, v46
	v_cvt_pk_bf16_f32 v116, v120, v121
	v_exp_f32_e32 v47, v47
	v_cvt_pk_bf16_f32 v117, v122, v123
	v_exp_f32_e32 v52, v52
	v_cvt_pk_bf16_f32 v118, v112, v113
	v_cvt_pk_bf16_f32 v119, v114, v115
	v_exp_f32_e32 v53, v53
	v_cvt_pk_bf16_f32 v100, v104, v105
	v_exp_f32_e32 v36, v36
	v_cvt_pk_bf16_f32 v101, v106, v107
	v_exp_f32_e32 v37, v37
	v_cvt_pk_bf16_f32 v102, v96, v97
	v_exp_f32_e32 v54, v54
	v_cvt_pk_bf16_f32 v103, v98, v99
	global_store_dwordx4 v[182:183], v[116:119], off
	v_exp_f32_e32 v55, v55
	v_lshl_add_u64 v[182:183], v[182:183], 0, s[98:99]
	v_exp_f32_e32 v38, v38
	global_store_dwordx4 v[182:183], v[100:103], off
	v_exp_f32_e32 v39, v39
	v_lshl_add_u64 v[182:183], v[182:183], 0, s[98:99]
	v_rcp_f32_e32 v92, v92
	v_pk_fma_f32 v[60:61], v[60:61], v[196:197], v[196:197] op_sel_hi:[1,0,0]
	v_pk_fma_f32 v[44:45], v[44:45], v[198:199], v[198:199] op_sel_hi:[1,0,0]
	v_rcp_f32_e32 v93, v93
	v_pk_fma_f32 v[62:63], v[62:63], v[196:197], v[196:197] op_sel_hi:[1,0,0]
	v_pk_fma_f32 v[46:47], v[46:47], v[198:199], v[198:199] op_sel_hi:[1,0,0]
	v_rcp_f32_e32 v76, v76
	v_pk_fma_f32 v[52:53], v[52:53], v[196:197], v[196:197] op_sel_hi:[1,0,0]
	v_pk_fma_f32 v[36:37], v[36:37], v[198:199], v[198:199] op_sel_hi:[1,0,0]
	v_rcp_f32_e32 v77, v77
	v_pk_fma_f32 v[54:55], v[54:55], v[196:197], v[196:197] op_sel_hi:[1,0,0]
	v_pk_fma_f32 v[38:39], v[38:39], v[198:199], v[198:199] op_sel_hi:[1,0,0]
	v_rcp_f32_e32 v94, v94
	v_mul_f32_e32 v178, 0xbfb8aa3b, v148
	v_mul_f32_e32 v179, v148, v148
	v_rcp_f32_e32 v95, v95
	v_mul_f32_e32 v180, 0xbfb8aa3b, v149
	v_mul_f32_e32 v181, v149, v149
	v_rcp_f32_e32 v78, v78
	v_pk_mul_f32 v[24:25], v[28:29], v[24:25]
	v_pk_mul_f32 v[8:9], v[12:13], v[8:9]
	v_rcp_f32_e32 v79, v79
	v_pk_mul_f32 v[26:27], v[30:31], v[26:27]
	v_rcp_f32_e32 v84, v84
	v_pk_mul_f32 v[10:11], v[14:15], v[10:11]
	v_pk_mul_f32 v[16:17], v[20:21], v[16:17]
	v_rcp_f32_e32 v85, v85
	v_pk_mul_f32 v[0:1], v[4:5], v[0:1]
	v_pk_mul_f32 v[18:19], v[22:23], v[18:19]
	v_rcp_f32_e32 v68, v68
	v_pk_mul_f32 v[2:3], v[6:7], v[2:3]
	v_rcp_f32_e32 v200, v179
	v_rcp_f32_e32 v69, v69
	v_rcp_f32_e32 v202, v181
	v_pk_mul_f32 v[28:29], v[28:29], v[178:179] op_sel_hi:[1,0]
	v_rcp_f32_e32 v86, v86
	v_pk_mul_f32 v[12:13], v[12:13], v[180:181] op_sel_hi:[1,0]
	v_pk_mul_f32 v[30:31], v[30:31], v[178:179] op_sel_hi:[1,0]
	v_rcp_f32_e32 v87, v87
	v_pk_mul_f32 v[14:15], v[14:15], v[180:181] op_sel_hi:[1,0]
	v_pk_mul_f32 v[20:21], v[20:21], v[178:179] op_sel_hi:[1,0]
	v_rcp_f32_e32 v70, v70
	v_pk_mul_f32 v[4:5], v[4:5], v[180:181] op_sel_hi:[1,0]
	v_pk_mul_f32 v[22:23], v[22:23], v[178:179] op_sel_hi:[1,0]
	v_rcp_f32_e32 v71, v71
	v_pk_mul_f32 v[6:7], v[6:7], v[180:181] op_sel_hi:[1,0]
	v_exp_f32_e32 v28, v28
	v_pk_mul_f32 v[88:89], v[88:89], v[92:93]
	v_pk_mul_f32 v[72:73], v[72:73], v[76:77]
	v_exp_f32_e32 v29, v29
	v_pk_mul_f32 v[90:91], v[90:91], v[94:95]
	v_exp_f32_e32 v12, v12
	v_pk_mul_f32 v[74:75], v[74:75], v[78:79]
	v_exp_f32_e32 v13, v13
	v_pk_mul_f32 v[80:81], v[80:81], v[84:85]
	v_exp_f32_e32 v30, v30
	v_pk_mul_f32 v[64:65], v[64:65], v[68:69]
	v_pk_mul_f32 v[82:83], v[82:83], v[86:87]
	v_exp_f32_e32 v31, v31
	v_pk_mul_f32 v[66:67], v[66:67], v[70:71]
	v_exp_f32_e32 v14, v14
	v_cvt_pk_bf16_f32 v84, v88, v89
	v_exp_f32_e32 v15, v15
	v_cvt_pk_bf16_f32 v85, v90, v91
	v_exp_f32_e32 v20, v20
	v_cvt_pk_bf16_f32 v86, v80, v81
	v_cvt_pk_bf16_f32 v87, v82, v83
	v_exp_f32_e32 v21, v21
	v_cvt_pk_bf16_f32 v68, v72, v73
	v_exp_f32_e32 v4, v4
	v_cvt_pk_bf16_f32 v69, v74, v75
	v_exp_f32_e32 v5, v5
	v_cvt_pk_bf16_f32 v70, v64, v65
	v_exp_f32_e32 v22, v22
	v_cvt_pk_bf16_f32 v71, v66, v67
	global_store_dwordx4 v[182:183], v[84:87], off
	v_exp_f32_e32 v23, v23
	v_lshl_add_u64 v[182:183], v[182:183], 0, s[98:99]
	v_exp_f32_e32 v6, v6
	global_store_dwordx4 v[182:183], v[68:71], off
	v_exp_f32_e32 v7, v7
	v_lshl_add_u64 v[182:183], v[182:183], 0, s[100:101]
	v_rcp_f32_e32 v60, v60
	v_pk_fma_f32 v[28:29], v[28:29], v[200:201], v[200:201] op_sel_hi:[1,0,0]
	v_rcp_f32_e32 v61, v61
	v_rcp_f32_e32 v44, v44
	v_pk_fma_f32 v[12:13], v[12:13], v[202:203], v[202:203] op_sel_hi:[1,0,0]
	v_rcp_f32_e32 v45, v45
	v_rcp_f32_e32 v62, v62
	v_pk_fma_f32 v[30:31], v[30:31], v[200:201], v[200:201] op_sel_hi:[1,0,0]
	v_rcp_f32_e32 v63, v63
	v_rcp_f32_e32 v46, v46
	v_pk_fma_f32 v[14:15], v[14:15], v[202:203], v[202:203] op_sel_hi:[1,0,0]
	v_rcp_f32_e32 v47, v47
	v_rcp_f32_e32 v52, v52
	v_pk_fma_f32 v[20:21], v[20:21], v[200:201], v[200:201] op_sel_hi:[1,0,0]
	v_rcp_f32_e32 v53, v53
	v_rcp_f32_e32 v36, v36
	v_pk_fma_f32 v[4:5], v[4:5], v[202:203], v[202:203] op_sel_hi:[1,0,0]
	v_rcp_f32_e32 v37, v37
	v_rcp_f32_e32 v54, v54
	v_pk_fma_f32 v[22:23], v[22:23], v[200:201], v[200:201] op_sel_hi:[1,0,0]
	v_rcp_f32_e32 v55, v55
	v_rcp_f32_e32 v38, v38
	v_pk_fma_f32 v[6:7], v[6:7], v[202:203], v[202:203] op_sel_hi:[1,0,0]
	v_rcp_f32_e32 v39, v39
	v_rcp_f32_e32 v28, v28
	v_pk_mul_f32 v[56:57], v[56:57], v[60:61]
	v_pk_mul_f32 v[40:41], v[40:41], v[44:45]
	v_rcp_f32_e32 v29, v29
	v_pk_mul_f32 v[58:59], v[58:59], v[62:63]
	v_rcp_f32_e32 v12, v12
	v_pk_mul_f32 v[42:43], v[42:43], v[46:47]
	v_rcp_f32_e32 v13, v13
	v_pk_mul_f32 v[48:49], v[48:49], v[52:53]
	v_rcp_f32_e32 v30, v30
	v_pk_mul_f32 v[32:33], v[32:33], v[36:37]
	v_pk_mul_f32 v[50:51], v[50:51], v[54:55]
	v_rcp_f32_e32 v31, v31
	v_pk_mul_f32 v[34:35], v[34:35], v[38:39]
	v_rcp_f32_e32 v14, v14
	v_cvt_pk_bf16_f32 v52, v56, v57
	v_rcp_f32_e32 v15, v15
	v_cvt_pk_bf16_f32 v53, v58, v59
	v_rcp_f32_e32 v20, v20
	v_cvt_pk_bf16_f32 v54, v48, v49
	v_cvt_pk_bf16_f32 v55, v50, v51
	v_rcp_f32_e32 v21, v21
	v_cvt_pk_bf16_f32 v36, v40, v41
	v_rcp_f32_e32 v4, v4
	v_cvt_pk_bf16_f32 v37, v42, v43
	v_rcp_f32_e32 v5, v5
	v_cvt_pk_bf16_f32 v38, v32, v33
	v_rcp_f32_e32 v22, v22
	v_cvt_pk_bf16_f32 v39, v34, v35
	global_store_dwordx4 v[182:183], v[52:55], off
	v_rcp_f32_e32 v23, v23
	v_lshl_add_u64 v[182:183], v[182:183], 0, s[98:99]
	v_rcp_f32_e32 v6, v6
	global_store_dwordx4 v[182:183], v[36:39], off
	v_rcp_f32_e32 v7, v7
	v_lshl_add_u64 v[182:183], v[182:183], 0, s[98:99]
	v_pk_mul_f32 v[24:25], v[24:25], v[28:29]
	v_pk_mul_f32 v[8:9], v[8:9], v[12:13]
	v_pk_mul_f32 v[26:27], v[26:27], v[30:31]
	v_pk_mul_f32 v[10:11], v[10:11], v[14:15]
	v_pk_mul_f32 v[16:17], v[16:17], v[20:21]
	v_pk_mul_f32 v[0:1], v[0:1], v[4:5]
	v_pk_mul_f32 v[18:19], v[18:19], v[22:23]
	v_pk_mul_f32 v[2:3], v[2:3], v[6:7]
	v_cvt_pk_bf16_f32 v20, v24, v25
	v_cvt_pk_bf16_f32 v21, v26, v27
	v_cvt_pk_bf16_f32 v22, v16, v17
	v_cvt_pk_bf16_f32 v23, v18, v19
	v_cvt_pk_bf16_f32 v4, v8, v9
	v_cvt_pk_bf16_f32 v5, v10, v11
	v_cvt_pk_bf16_f32 v6, v0, v1
	v_cvt_pk_bf16_f32 v7, v2, v3
	global_store_dwordx4 v[182:183], v[20:23], off
	v_lshl_add_u64 v[182:183], v[182:183], 0, s[98:99]
	global_store_dwordx4 v[182:183], v[4:7], off
	s_andn2_b64 vcc, exec, s[4:5]
	s_mov_b64 s[4:5], -1
	s_cbranch_vccnz .LBB0_2188
	s_andn2_b64 vcc, exec, s[8:9]
	s_cbranch_vccnz .LBB0_2187
	s_barrier
	s_branch .LBB0_2187
